# attention unit epilogue: z_a loads issued at the tile-loop exit and gamma/z loads batched with counted waits, on top of v69
# speedup vs baseline: 1.0592x; 1.0005x over previous
; #define LAS __attribute__((address_space(3)))
; __device__ __forceinline__ unsigned cvtpk_s(float lo, float hi) { f32x2_t v = {lo, hi}; bf16x2_t b = __builtin_convertvector(v, bf16x2_t); return __builtin_bit_cast(unsigned, b); }
; #define ATT_GD(ms, dvb) do { \
;         const v4i16_t lo_ = ATT_VTR(vb_ + (ms) * 16 * 320 + (dvb) * 64), hh_ = ATT_VTR(vb_ + ((ms) * 16 + 8) * 320 + (dvb) * 64); \
;         const bf16x8 vf_ = (bf16x8){lo_[0], lo_[1], lo_[2], lo_[3], hh_[0], hh_[1], hh_[2], hh_[3]}; \
;         o[dvb] = ATT_MFMA(vf_, __builtin_bit_cast(bf16x8, pw##ms), o[dvb]); } while (0)
; __device__ __forceinline__ void attn_unit(LAS unsigned char* lds, const bf16_t* PROJ, bf16_t* OCAT, const float* subg, float lam, float oml, int b, int h, int qb) {
;     ...
;     {
;         float sacc = 0.f;
; #pragma unroll
;         for (int r = 0; r < 16; ++r) sacc += pB0[r] + pB1[r];
;         lrun += sacc;
;         u32x4 pw0, pw1, pw2, pw3;
;         pw0.x = cvtpk_s(pB0[0], pB0[1]); pw0.y = cvtpk_s(pB0[2], pB0[3]); pw0.z = cvtpk_s(pB0[4], pB0[5]); pw0.w = cvtpk_s(pB0[6], pB0[7]);
;         pw1.x = cvtpk_s(pB0[8], pB0[9]); pw1.y = cvtpk_s(pB0[10], pB0[11]); pw1.z = cvtpk_s(pB0[12], pB0[13]); pw1.w = cvtpk_s(pB0[14], pB0[15]);
;         pw2.x = cvtpk_s(pB1[0], pB1[1]); pw2.y = cvtpk_s(pB1[2], pB1[3]); pw2.z = cvtpk_s(pB1[4], pB1[5]); pw2.w = cvtpk_s(pB1[6], pB1[7]);
;         pw3.x = cvtpk_s(pB1[8], pB1[9]); pw3.y = cvtpk_s(pB1[10], pB1[11]); pw3.z = cvtpk_s(pB1[12], pB1[13]); pw3.w = cvtpk_s(pB1[14], pB1[15]);
;         const LAS unsigned char* vb_ = lds + vs_prev + vread;
;     ...
;         ATT_GD(0, 0); ATT_GD(0, 1); ATT_GD(0, 2); ATT_GD(0, 3); ATT_GD(1, 0); ATT_GD(1, 1); ATT_GD(1, 2); ATT_GD(1, 3);
;         ATT_GD(2, 0); ATT_GD(2, 1); ATT_GD(2, 2); ATT_GD(2, 3); ATT_GD(3, 0); ATT_GD(3, 1); ATT_GD(3, 2); ATT_GD(3, 3);
;     ...
;     }
;     __syncthreads();
.LBB0_455:
	v_add_f32_e32 v80, v112, v64
	v_add_f32_e32 v80, 0, v80
	v_add_f32_e32 v81, v113, v65
	v_add_f32_e32 v80, v81, v80
	v_add_f32_e32 v81, v114, v66
	v_add_f32_e32 v80, v81, v80
	v_add_f32_e32 v81, v115, v67
	v_add_f32_e32 v80, v81, v80
	v_add_f32_e32 v81, v116, v68
	v_add_f32_e32 v80, v81, v80
	v_add_f32_e32 v81, v117, v69
	v_add_f32_e32 v80, v81, v80
	v_add_f32_e32 v81, v118, v70
	v_add_f32_e32 v80, v81, v80
	v_add_f32_e32 v81, v119, v71
	v_add_f32_e32 v80, v81, v80
	v_add_f32_e32 v81, v120, v72
	v_add_f32_e32 v80, v81, v80
	v_add_f32_e32 v81, v121, v73
	v_add_f32_e32 v80, v81, v80
	v_add_f32_e32 v81, v122, v74
	v_add_f32_e32 v80, v81, v80
	v_add_f32_e32 v81, v123, v75
	v_add_f32_e32 v82, v81, v80
	v_pk_add_f32 v[80:81], v[124:125], v[76:77]
	v_cvt_pk_bf16_f32 v83, v70, v71
	v_add_f32_e32 v80, v80, v82
	v_add_f32_e32 v82, v81, v80
	v_pk_add_f32 v[80:81], v[126:127], v[78:79]
	v_cvt_pk_bf16_f32 v90, v112, v113
	v_add_f32_e32 v80, v80, v82
	v_add_f32_e32 v80, v81, v80
	v_add_f32_e32 v88, v145, v80
	v_cvt_pk_bf16_f32 v80, v64, v65
	v_cvt_pk_bf16_f32 v64, v72, v73
	ds_read_b64_tr_b16 v[70:71], v160 offset:61440
	ds_read_b64_tr_b16 v[72:73], v160 offset:64000
	v_cvt_pk_bf16_f32 v91, v114, v115
	v_cvt_pk_bf16_f32 v92, v116, v117
	v_cvt_pk_bf16_f32 v93, v118, v119
	v_cvt_pk_bf16_f32 v82, v68, v69
	v_add_u32_e32 v68, 0xf000, v160
	s_waitcnt lgkmcnt(0)
	v_mfma_f32_32x32x16_bf16 v[0:15], v[70:73], v[90:93], v[0:15]
	ds_read_b64_tr_b16 v[70:71], v160 offset:61504
	ds_read_b64_tr_b16 v[72:73], v160 offset:64064
	v_cvt_pk_bf16_f32 v84, v120, v121
	v_cvt_pk_bf16_f32 v85, v122, v123
	v_cvt_pk_bf16_f32 v86, v124, v125
	v_cvt_pk_bf16_f32 v87, v126, v127
	v_cvt_pk_bf16_f32 v81, v66, v67
	v_cvt_pk_bf16_f32 v65, v74, v75
	s_waitcnt lgkmcnt(0)
	v_mfma_f32_32x32x16_bf16 v[48:63], v[70:73], v[90:93], v[48:63]
	ds_read_b64_tr_b16 v[70:71], v160 offset:61568
	ds_read_b64_tr_b16 v[72:73], v160 offset:64128
	v_cvt_pk_bf16_f32 v66, v76, v77
	v_cvt_pk_bf16_f32 v67, v78, v79
	s_lshl_b32 s70, s69, 1
	s_add_u32 s16, s48, s70
	s_addc_u32 s17, s49, 0
	s_cmp_eq_u32 s84, 1
	s_waitcnt lgkmcnt(0)
	v_mfma_f32_32x32x16_bf16 v[32:47], v[70:73], v[90:93], v[32:47]
	ds_read_b64_tr_b16 v[70:71], v160 offset:61632
	ds_read_b64_tr_b16 v[72:73], v160 offset:64192
	s_mul_i32 s84, s84, 0x10800
	s_cselect_b64 s[4:5], -1, 0
	s_add_i32 s18, s84, 0
	s_add_i32 s65, s65, s34
	s_add_i32 s64, s64, s34
	s_cmpk_gt_i32 s65, 0x3ff
	s_waitcnt lgkmcnt(0)
	v_mfma_f32_32x32x16_bf16 v[16:31], v[70:73], v[90:93], v[16:31]
	ds_read_b64_tr_b16 v[70:71], v68 offset:5120
	ds_read_b64_tr_b16 v[72:73], v68 offset:7680
	s_waitcnt lgkmcnt(0)
	v_mfma_f32_32x32x16_bf16 v[0:15], v[70:73], v[84:87], v[0:15]
	ds_read_b64_tr_b16 v[70:71], v68 offset:5184
	ds_read_b64_tr_b16 v[72:73], v68 offset:7744
	s_waitcnt lgkmcnt(0)
	v_mfma_f32_32x32x16_bf16 v[48:63], v[70:73], v[84:87], v[48:63]
	ds_read_b64_tr_b16 v[70:71], v68 offset:5248
	ds_read_b64_tr_b16 v[72:73], v68 offset:7808
	s_waitcnt lgkmcnt(0)
	v_mfma_f32_32x32x16_bf16 v[32:47], v[70:73], v[84:87], v[32:47]
	ds_read_b64_tr_b16 v[70:71], v68 offset:5312
	ds_read_b64_tr_b16 v[72:73], v68 offset:7872
	s_waitcnt lgkmcnt(0)
	v_mfma_f32_32x32x16_bf16 v[16:31], v[70:73], v[84:87], v[16:31]
	ds_read_b64_tr_b16 v[70:71], v68 offset:10240
	ds_read_b64_tr_b16 v[72:73], v68 offset:12800
	s_waitcnt lgkmcnt(0)
	v_mfma_f32_32x32x16_bf16 v[0:15], v[70:73], v[80:83], v[0:15]
	ds_read_b64_tr_b16 v[70:71], v68 offset:10304
	ds_read_b64_tr_b16 v[72:73], v68 offset:12864
	s_waitcnt lgkmcnt(0)
	v_mfma_f32_32x32x16_bf16 v[48:63], v[70:73], v[80:83], v[48:63]
	ds_read_b64_tr_b16 v[70:71], v68 offset:10368
	ds_read_b64_tr_b16 v[72:73], v68 offset:12928
	s_waitcnt lgkmcnt(0)
	v_mfma_f32_32x32x16_bf16 v[32:47], v[70:73], v[80:83], v[32:47]
	ds_read_b64_tr_b16 v[70:71], v68 offset:10432
	ds_read_b64_tr_b16 v[72:73], v68 offset:12992
	s_waitcnt lgkmcnt(0)
	v_mfma_f32_32x32x16_bf16 v[16:31], v[70:73], v[80:83], v[16:31]
	ds_read_b64_tr_b16 v[70:71], v68 offset:15360
	ds_read_b64_tr_b16 v[72:73], v68 offset:17920
	s_waitcnt lgkmcnt(0)
	v_mfma_f32_32x32x16_bf16 v[0:15], v[70:73], v[64:67], v[0:15]
	ds_read_b64_tr_b16 v[70:71], v68 offset:15424
	ds_read_b64_tr_b16 v[72:73], v68 offset:17984
	s_waitcnt lgkmcnt(0)
	v_mfma_f32_32x32x16_bf16 v[48:63], v[70:73], v[64:67], v[48:63]
	ds_read_b64_tr_b16 v[70:71], v68 offset:15488
	ds_read_b64_tr_b16 v[72:73], v68 offset:18048
	s_waitcnt lgkmcnt(0)
	v_mfma_f32_32x32x16_bf16 v[32:47], v[70:73], v[64:67], v[32:47]
	ds_read_b64_tr_b16 v[70:71], v68 offset:15552
	ds_read_b64_tr_b16 v[72:73], v68 offset:18112
	s_waitcnt lgkmcnt(0)
	s_barrier
; #define LAS __attribute__((address_space(3)))
; __device__ __forceinline__ float half_sum(float m) { auto rr = __builtin_amdgcn_permlane32_swap(__float_as_uint(m), __float_as_uint(m), false, false); return __uint_as_float(rr[0]) + __uint_as_float(rr[1]); }
; __device__ __forceinline__ void attn_unit(LAS unsigned char* lds, const bf16_t* PROJ, bf16_t* OCAT, const float* subg, float lam, float oml, int b, int h, int qb) {
;     ...
;         const float ltot = half_sum(lrun);
;         float inv = 1.0f / ltot; if (comp == 1) inv *= lam;
;         LAS float* cb = (LAS float*)lds + comp * (128 * 132) + (wq * 32 + r32) * 132 + 4 * hi;
; #pragma unroll
;         for (int dvb = 0; dvb < 4; ++dvb)
; #pragma unroll
;             for (int k4 = 0; k4 < 4; ++k4) {
;                 const f32x4 v = (f32x4){o[dvb][4 * k4 + 0] * inv, o[dvb][4 * k4 + 1] * inv, o[dvb][4 * k4 + 2] * inv, o[dvb][4 * k4 + 3] * inv};
;                 *(LAS f32x4*)(cb + dvb * 32 + 8 * k4) = v;
;             }
;     }
;     __syncthreads();
;     {
;         const int q2 = tid >> 2, part = tid & 3;
;         const LAS float* a0 = (const LAS float*)lds + q2 * 132 + part * 32; const LAS float* a1 = a0 + 128 * 132;
;         f32x4 a[8]; float ss = 0.f;
; #pragma unroll
;         for (int i = 0; i < 8; ++i) { a[i] = *(const LAS f32x4*)(a0 + 4 * i) - *(const LAS f32x4*)(a1 + 4 * i); ss += (a[i].x * a[i].x + a[i].y * a[i].y) + (a[i].z * a[i].z + a[i].w * a[i].w); }
;         ss += __shfl_xor(ss, 1); ss += __shfl_xor(ss, 2);
;         const float rs = rsqrtf(ss * (1.0f / 128.0f) + EPS) * oml;
	v_mfma_f32_32x32x16_bf16 v[16:31], v[70:73], v[64:67], v[16:31]
	v_mul_u32_u24_e32 v64, 0x210, v240
	v_lshlrev_b32_e32 v65, 2, v224
	v_lshlrev_b32_e32 v66, 5, v239
	v_add3_u32 v71, s18, v64, v65
	v_ashrrev_i32_e32 v64, 2, v239
	s_movk_i32 s18, 0x210
	v_and_b32_e32 v74, 0x60, v66
	v_mul_lo_u32 v65, v64, s18
	v_lshlrev_b32_e32 v68, 2, v74
	v_and_b32_e32 v66, 64, v235
	v_add3_u32 v70, 0, v65, v68
	v_xor_b32_e32 v65, 1, v235
	v_add_u32_e32 v66, 64, v66
	v_cmp_lt_i32_e32 vcc, v65, v66
	v_lshlrev_b32_e32 v224, 1, v74
	s_nop 0
	v_cndmask_b32_e32 v75, v235, v65, vcc
	v_xor_b32_e32 v65, 2, v235
	v_cmp_lt_i32_e32 vcc, v65, v66
	v_mov_b64_e32 v[66:67], s[6:7]
	s_nop 0
	v_cndmask_b32_e32 v69, v235, v65, vcc
	v_ashrrev_i32_e32 v65, 31, v64
	v_lshl_add_u64 v[64:65], s[82:83], 0, v[64:65]
	v_mad_u64_u32 v[66:67], s[18:19], v64, s52, v[66:67]
	v_mov_b32_e32 v72, v67
	v_mad_u64_u32 v[72:73], s[18:19], v65, s52, v[72:73]
	v_mov_b32_e32 v67, v72
	v_mov_b32_e32 v72, v88
	s_nop 1
	v_permlane32_swap_b32_e32 v88, v72
	v_lshlrev_b64 v[64:65], 12, v[64:65]
	v_add_f32_e32 v72, v88, v72
	v_lshl_add_u64 v[64:65], s[16:17], 0, v[64:65]
	v_div_scale_f32 v73, s[16:17], v72, v72, 1.0
	v_rcp_f32_e32 v74, v73
	v_lshl_add_u64 v[64:65], v[64:65], 0, v[224:225]
	v_fma_f32 v76, -v73, v74, 1.0
	v_fmac_f32_e32 v74, v76, v74
	v_div_scale_f32 v76, vcc, 1.0, v72, 1.0
	v_mul_f32_e32 v77, v76, v74
	v_fma_f32 v78, -v73, v77, v76
	v_fmac_f32_e32 v77, v78, v74
	v_fma_f32 v73, -v73, v77, v76
	v_div_fmas_f32 v73, v73, v74, v77
	v_div_fixup_f32 v72, v73, v72, 1.0
	v_mul_f32_e32 v73, v237, v72
	v_cndmask_b32_e64 v72, v72, v73, s[4:5]
	v_pk_mul_f32 v[0:1], v[0:1], v[72:73] op_sel_hi:[1,0]
	v_pk_mul_f32 v[2:3], v[2:3], v[72:73] op_sel_hi:[1,0]
	ds_write_b128 v71, v[0:3]
	v_pk_mul_f32 v[0:1], v[4:5], v[72:73] op_sel_hi:[1,0]
	v_pk_mul_f32 v[2:3], v[6:7], v[72:73] op_sel_hi:[1,0]
	ds_write_b128 v71, v[0:3] offset:32
	v_pk_mul_f32 v[0:1], v[8:9], v[72:73] op_sel_hi:[1,0]
	v_pk_mul_f32 v[2:3], v[10:11], v[72:73] op_sel_hi:[1,0]
	ds_write_b128 v71, v[0:3] offset:64
	v_pk_mul_f32 v[0:1], v[12:13], v[72:73] op_sel_hi:[1,0]
	v_pk_mul_f32 v[2:3], v[14:15], v[72:73] op_sel_hi:[1,0]
	ds_write_b128 v71, v[0:3] offset:96
	v_pk_mul_f32 v[0:1], v[48:49], v[72:73] op_sel_hi:[1,0]
	v_pk_mul_f32 v[2:3], v[50:51], v[72:73] op_sel_hi:[1,0]
	ds_write_b128 v71, v[0:3] offset:128
	v_pk_mul_f32 v[0:1], v[52:53], v[72:73] op_sel_hi:[1,0]
	v_pk_mul_f32 v[2:3], v[54:55], v[72:73] op_sel_hi:[1,0]
	ds_write_b128 v71, v[0:3] offset:160
	v_pk_mul_f32 v[0:1], v[56:57], v[72:73] op_sel_hi:[1,0]
	v_pk_mul_f32 v[2:3], v[58:59], v[72:73] op_sel_hi:[1,0]
	ds_write_b128 v71, v[0:3] offset:192
	v_pk_mul_f32 v[0:1], v[60:61], v[72:73] op_sel_hi:[1,0]
	v_pk_mul_f32 v[2:3], v[62:63], v[72:73] op_sel_hi:[1,0]
	ds_write_b128 v71, v[0:3] offset:224
	v_pk_mul_f32 v[0:1], v[32:33], v[72:73] op_sel_hi:[1,0]
	v_pk_mul_f32 v[2:3], v[34:35], v[72:73] op_sel_hi:[1,0]
	ds_write_b128 v71, v[0:3] offset:256
	v_pk_mul_f32 v[0:1], v[36:37], v[72:73] op_sel_hi:[1,0]
	v_pk_mul_f32 v[2:3], v[38:39], v[72:73] op_sel_hi:[1,0]
	ds_write_b128 v71, v[0:3] offset:288
	v_pk_mul_f32 v[0:1], v[40:41], v[72:73] op_sel_hi:[1,0]
	v_pk_mul_f32 v[2:3], v[42:43], v[72:73] op_sel_hi:[1,0]
	ds_write_b128 v71, v[0:3] offset:320
	v_pk_mul_f32 v[0:1], v[44:45], v[72:73] op_sel_hi:[1,0]
	v_pk_mul_f32 v[2:3], v[46:47], v[72:73] op_sel_hi:[1,0]
	ds_write_b128 v71, v[0:3] offset:352
	v_pk_mul_f32 v[0:1], v[16:17], v[72:73] op_sel_hi:[1,0]
	v_pk_mul_f32 v[2:3], v[18:19], v[72:73] op_sel_hi:[1,0]
	ds_write_b128 v71, v[0:3] offset:384
	v_pk_mul_f32 v[0:1], v[20:21], v[72:73] op_sel_hi:[1,0]
	v_pk_mul_f32 v[2:3], v[22:23], v[72:73] op_sel_hi:[1,0]
	ds_write_b128 v71, v[0:3] offset:416
	v_pk_mul_f32 v[0:1], v[24:25], v[72:73] op_sel_hi:[1,0]
	v_pk_mul_f32 v[2:3], v[26:27], v[72:73] op_sel_hi:[1,0]
	ds_write_b128 v71, v[0:3] offset:448
	v_pk_mul_f32 v[0:1], v[28:29], v[72:73] op_sel_hi:[1,0]
	v_pk_mul_f32 v[2:3], v[30:31], v[72:73] op_sel_hi:[1,0]
	ds_write_b128 v71, v[0:3] offset:480
	v_add_u32_e32 v10, 0x10800, v70
	s_waitcnt lgkmcnt(0)
	s_barrier
	ds_read_b128 v[2:5], v70
	ds_read_b128 v[6:9], v70 offset:16
	ds_read_b128 v[14:17], v70 offset:32
	ds_read_b128 v[18:21], v70 offset:48
	ds_read_b128 v[22:25], v10
	v_lshlrev_b32_e32 v48, 2, v75
	v_lshl_add_u64 v[0:1], v[66:67], 0, s[70:71]
	v_lshl_add_u64 v[0:1], v[0:1], 0, v[224:225]
	s_mov_b64 s[4:5], 0x1800
	s_waitcnt lgkmcnt(0)
	v_sub_f32_e32 v42, v2, v22
	v_add_u32_e32 v2, 0x10810, v70
	v_sub_f32_e32 v41, v5, v25
	v_sub_f32_e32 v40, v4, v24
	v_sub_f32_e32 v43, v3, v23
	ds_read_b128 v[2:5], v2
	v_lshl_add_u64 v[12:13], v[0:1], 0, s[4:5]
	global_load_dwordx4 v[180:183], v68, s[8:9]
	global_load_dwordx4 v[184:187], v68, s[8:9] offset:16
	global_load_dwordx4 v[188:191], v68, s[8:9] offset:32
	global_load_dwordx4 v[192:195], v68, s[8:9] offset:48
	global_load_dwordx4 v[196:199], v68, s[8:9] offset:64
	global_load_dwordx4 v[200:203], v68, s[8:9] offset:80
	global_load_dwordx4 v[204:207], v68, s[8:9] offset:96
	global_load_dwordx4 v[208:211], v68, s[8:9] offset:112
	s_movk_i32 s4, 0x1000
	s_waitcnt lgkmcnt(0)
	v_sub_f32_e32 v47, v7, v3
	v_sub_f32_e32 v45, v9, v5
	v_sub_f32_e32 v44, v8, v4
	v_sub_f32_e32 v46, v6, v2
	v_mov_b32_e32 v4, v43
	v_mov_b32_e32 v5, v47
	v_mov_b32_e32 v2, v42
	v_mov_b32_e32 v3, v46
	v_pk_mul_f32 v[4:5], v[4:5], v[4:5]
	v_mov_b32_e32 v6, v41
	v_mov_b32_e32 v7, v45
	v_pk_fma_f32 v[2:3], v[2:3], v[2:3], v[4:5]
	v_mov_b32_e32 v4, v40
	v_mov_b32_e32 v5, v44
	v_pk_mul_f32 v[6:7], v[6:7], v[6:7]
	s_nop 0
	v_pk_fma_f32 v[4:5], v[4:5], v[4:5], v[6:7]
	s_nop 0
	v_pk_add_f32 v[10:11], v[2:3], v[4:5]
	v_add_u32_e32 v2, 0x10820, v70
	ds_read_b128 v[2:5], v2
	s_waitcnt lgkmcnt(0)
; #define LAS __attribute__((address_space(3)))
; __device__ __forceinline__ unsigned cvt_pk_bf16(float lo, float hi) { unsigned r; asm volatile("v_cvt_pk_bf16_f32 %0, %1, %2" : "=v"(r) : "v"(lo), "v"(hi)); return r; }
; __device__ __forceinline__ float bflo(unsigned w) { return __uint_as_float(w << 16); }
; __device__ __forceinline__ float bfhi(unsigned w) { return __uint_as_float(w & 0xffff0000u); }
; __device__ __forceinline__ float silu_f(float z) { return z / (1.0f + __expf(-z)); }
; __device__ __forceinline__ void attn_unit(LAS unsigned char* lds, const bf16_t* PROJ, bf16_t* OCAT, const float* subg, float lam, float oml, int b, int h, int qb) {
;     ...
;     {
;         const int q2 = tid >> 2, part = tid & 3;
;         const LAS float* a0 = (const LAS float*)lds + q2 * 132 + part * 32; const LAS float* a1 = a0 + 128 * 132;
;         f32x4 a[8]; float ss = 0.f;
; #pragma unroll
;         for (int i = 0; i < 8; ++i) { a[i] = *(const LAS f32x4*)(a0 + 4 * i) - *(const LAS f32x4*)(a1 + 4 * i); ss += (a[i].x * a[i].x + a[i].y * a[i].y) + (a[i].z * a[i].z + a[i].w * a[i].w); }
;         ss += __shfl_xor(ss, 1); ss += __shfl_xor(ss, 2);
;         const float rs = rsqrtf(ss * (1.0f / 128.0f) + EPS) * oml;
;         const size_t row = rowbase + q0 + q2;
;         const bf16_t* zp = PROJ + row * PP + C_ZA + h * 128 + part * 32; bf16_t* op = OCAT + row * 2048 + h * 128 + part * 32; const float* gp = subg + part * 32;
; #pragma unroll
;         for (int i = 0; i < 4; ++i) {
;             const u32x4 z = *(const u32x4*)(zp + 8 * i); const f32x4 ga = *(const f32x4*)(gp + 8 * i), gb = *(const f32x4*)(gp + 8 * i + 4);
;             const f32x4 xa = a[2 * i] * rs * ga, xb = a[2 * i + 1] * rs * gb;
;             u32x4 w; w.x = cvt_pk_bf16(xa.x * silu_f(bflo(z.x)), xa.y * silu_f(bfhi(z.x))); w.y = cvt_pk_bf16(xa.z * silu_f(bflo(z.y)), xa.w * silu_f(bfhi(z.y)));
;             w.z = cvt_pk_bf16(xb.x * silu_f(bflo(z.z)), xb.y * silu_f(bfhi(z.z))); w.w = cvt_pk_bf16(xb.z * silu_f(bflo(z.w)), xb.w * silu_f(bfhi(z.w)));
;             *(u32x4*)(op + 8 * i) = w;
;         }
	v_sub_f32_e32 v33, v15, v3
	v_sub_f32_e32 v32, v14, v2
	v_sub_f32_e32 v35, v17, v5
	v_sub_f32_e32 v34, v16, v4
	v_pk_mul_f32 v[2:3], v[34:35], v[34:35]
	v_pk_mul_f32 v[4:5], v[32:33], v[32:33]
	s_nop 0
	v_pk_mov_b32 v[6:7], v[4:5], v[2:3] op_sel:[1,0]
	v_mov_b32_e32 v5, v3
	v_add_u32_e32 v2, 0x10830, v70
	v_pk_add_f32 v[14:15], v[6:7], v[4:5]
	ds_read_b128 v[2:5], v2
	v_add_u32_e32 v6, 0x10840, v70
	ds_read_b128 v[6:9], v6
	s_waitcnt lgkmcnt(1)
	v_sub_f32_e32 v37, v19, v3
	v_sub_f32_e32 v36, v18, v2
	v_sub_f32_e32 v39, v21, v5
	v_sub_f32_e32 v38, v20, v4
	ds_read_b128 v[2:5], v70 offset:64
	s_waitcnt lgkmcnt(0)
	v_sub_f32_e32 v26, v2, v6
	v_sub_f32_e32 v24, v4, v8
	v_sub_f32_e32 v27, v3, v7
	v_mul_f32_e32 v4, v26, v26
	v_pk_add_f32 v[2:3], v[10:11], v[10:11] op_sel:[0,1] op_sel_hi:[1,0]
	v_sub_f32_e32 v25, v5, v9
	v_mul_f32_e32 v6, v27, v27
	v_mov_b32_e32 v3, v4
	v_pk_add_f32 v[4:5], v[14:15], v[14:15] op_sel:[0,1] op_sel_hi:[1,0]
	v_mul_f32_e32 v7, v24, v24
	v_mov_b32_e32 v5, v6
	v_pk_add_f32 v[2:3], v[2:3], v[4:5]
	v_mul_f32_e32 v4, v37, v37
	v_pk_fma_f32 v[4:5], v[36:37], v[36:37], v[4:5] op_sel_hi:[1,1,0]
	v_mul_f32_e32 v6, v39, v39
	v_mul_f32_e32 v8, v25, v25
	v_mov_b32_e32 v5, v7
	v_pk_fma_f32 v[6:7], v[38:39], v[38:39], v[6:7] op_sel_hi:[1,1,0]
	s_nop 0
	v_mov_b32_e32 v7, v8
	v_pk_add_f32 v[4:5], v[4:5], v[6:7]
	v_add_u32_e32 v6, 0x10850, v70
	v_pk_add_f32 v[10:11], v[2:3], v[4:5]
	ds_read_b128 v[2:5], v70 offset:80
	ds_read_b128 v[6:9], v6
	s_waitcnt lgkmcnt(0)
	v_sub_f32_e32 v29, v3, v7
	v_sub_f32_e32 v28, v2, v6
	v_sub_f32_e32 v31, v5, v9
	v_sub_f32_e32 v30, v4, v8
	v_pk_mul_f32 v[2:3], v[30:31], v[30:31]
	v_pk_mul_f32 v[4:5], v[28:29], v[28:29]
	s_nop 0
	v_pk_mov_b32 v[6:7], v[4:5], v[2:3] op_sel:[1,0]
	v_mov_b32_e32 v5, v3
	v_pk_add_f32 v[22:23], v[6:7], v[4:5]
	v_add_u32_e32 v6, 0x10860, v70
	ds_read_b128 v[2:5], v70 offset:96
	ds_read_b128 v[6:9], v6
	s_waitcnt lgkmcnt(0)
	v_sub_f32_e32 v14, v2, v6
	v_add_u32_e32 v6, 0x10870, v70
	v_sub_f32_e32 v15, v3, v7
	v_sub_f32_e32 v17, v5, v9
	v_sub_f32_e32 v16, v4, v8
	ds_read_b128 v[2:5], v70 offset:112
	ds_read_b128 v[6:9], v6
	s_waitcnt lgkmcnt(0)
	v_sub_f32_e32 v20, v2, v6
	v_sub_f32_e32 v18, v4, v8
	v_sub_f32_e32 v21, v3, v7
	v_mul_f32_e32 v4, v20, v20
	v_pk_add_f32 v[2:3], v[10:11], v[10:11] op_sel:[0,1] op_sel_hi:[1,0]
	v_sub_f32_e32 v19, v5, v9
	v_mul_f32_e32 v6, v21, v21
	v_mov_b32_e32 v3, v4
	v_pk_add_f32 v[4:5], v[22:23], v[22:23] op_sel:[0,1] op_sel_hi:[1,0]
	v_mul_f32_e32 v7, v18, v18
	v_mov_b32_e32 v5, v6
	v_pk_add_f32 v[2:3], v[2:3], v[4:5]
	v_mul_f32_e32 v4, v15, v15
	v_pk_fma_f32 v[4:5], v[14:15], v[14:15], v[4:5] op_sel_hi:[1,1,0]
	v_mul_f32_e32 v6, v17, v17
	v_mul_f32_e32 v8, v19, v19
	v_mov_b32_e32 v5, v7
	v_pk_fma_f32 v[6:7], v[16:17], v[16:17], v[6:7] op_sel_hi:[1,1,0]
	s_nop 0
	v_mov_b32_e32 v7, v8
	v_pk_add_f32 v[4:5], v[4:5], v[6:7]
	s_nop 0
	v_pk_add_f32 v[2:3], v[2:3], v[4:5]
	s_nop 0
	v_add_f32_e32 v2, v2, v3
	ds_bpermute_b32 v4, v48, v2
	v_lshlrev_b32_e32 v3, 2, v69
	s_waitcnt lgkmcnt(0)
	v_add_f32_e32 v2, v2, v4
	ds_bpermute_b32 v3, v3, v2
	s_waitcnt lgkmcnt(0)
	v_add_f32_e32 v2, v2, v3
	v_mov_b32_e32 v3, 0x358637bd
	v_fmamk_f32 v2, v2, 0x3c000000, v3
	v_cmp_gt_f32_e32 vcc, s62, v2
	v_mul_f32_e32 v3, 0x4b800000, v2
	s_nop 0
	v_cndmask_b32_e32 v2, v2, v3, vcc
	v_rsq_f32_e32 v2, v2
	s_nop 0
	v_mul_f32_e32 v3, 0x45800000, v2
	v_cndmask_b32_e32 v2, v2, v3, vcc
	v_add_co_u32_e32 v0, vcc, s4, v0
	v_mul_f32_e32 v22, v238, v2
	s_nop 0
	v_addc_co_u32_e32 v1, vcc, 0, v1, vcc
	v_pk_mul_f32 v[42:43], v[42:43], v[22:23] op_sel_hi:[1,0]
	v_pk_mul_f32 v[40:41], v[40:41], v[22:23] op_sel_hi:[1,0]
	s_waitcnt vmcnt(0)
	v_mov_b64_e32 v[0:1], v[164:165]
	v_mov_b64_e32 v[2:3], v[166:167]
	v_mov_b64_e32 v[4:5], v[184:185]
	v_mov_b64_e32 v[6:7], v[186:187]
	v_mov_b64_e32 v[8:9], v[180:181]
	v_mov_b64_e32 v[10:11], v[182:183]
	v_pk_mul_f32 v[8:9], v[8:9], v[42:43]
	v_pk_mul_f32 v[10:11], v[10:11], v[40:41]
	v_pk_mul_f32 v[40:41], v[46:47], v[22:23] op_sel_hi:[1,0]
	v_pk_mul_f32 v[42:43], v[44:45], v[22:23] op_sel_hi:[1,0]
	v_lshlrev_b32_e32 v23, 16, v0
	v_pk_mul_f32 v[4:5], v[4:5], v[40:41]
	v_mul_f32_e32 v40, 0xbfb8aa3b, v23
	v_exp_f32_e32 v40, v40
	v_pk_mul_f32 v[6:7], v[6:7], v[42:43]
	v_and_b32_e32 v0, 0xffff0000, v0
	v_add_f32_e32 v40, 1.0, v40
	v_div_scale_f32 v41, s[4:5], v40, v40, v23
	v_rcp_f32_e32 v42, v41
	s_nop 0
	v_fma_f32 v43, -v41, v42, 1.0
	v_fmac_f32_e32 v42, v43, v42
	v_div_scale_f32 v43, vcc, v23, v40, v23
	v_mul_f32_e32 v44, v43, v42
	v_fma_f32 v45, -v41, v44, v43
	v_fmac_f32_e32 v44, v45, v42
	v_fma_f32 v41, -v41, v44, v43
	v_div_fmas_f32 v41, v41, v42, v44
	v_div_fixup_f32 v23, v41, v40, v23
	v_mul_f32_e32 v8, v23, v8
	v_mul_f32_e32 v23, 0xbfb8aa3b, v0
	v_exp_f32_e32 v23, v23
	s_nop 0
	v_add_f32_e32 v23, 1.0, v23
	v_div_scale_f32 v40, s[4:5], v23, v23, v0
	v_rcp_f32_e32 v41, v40
	s_nop 0
	v_fma_f32 v42, -v40, v41, 1.0
	v_fmac_f32_e32 v41, v42, v41
	v_div_scale_f32 v42, vcc, v0, v23, v0
	v_mul_f32_e32 v43, v42, v41
	v_fma_f32 v44, -v40, v43, v42
	v_fmac_f32_e32 v43, v44, v41
	v_fma_f32 v40, -v40, v43, v42
	v_div_fmas_f32 v40, v40, v41, v43
	v_div_fixup_f32 v0, v40, v23, v0
	v_mul_f32_e32 v0, v0, v9
	v_cvt_pk_bf16_f32 v0, v8, v0
	v_lshlrev_b32_e32 v8, 16, v1
	v_mul_f32_e32 v9, 0xbfb8aa3b, v8
	v_exp_f32_e32 v9, v9
	v_and_b32_e32 v1, 0xffff0000, v1
	v_add_f32_e32 v9, 1.0, v9
	v_div_scale_f32 v23, s[4:5], v9, v9, v8
	v_rcp_f32_e32 v40, v23
	s_nop 0
	v_fma_f32 v41, -v23, v40, 1.0
	v_fmac_f32_e32 v40, v41, v40
	v_div_scale_f32 v41, vcc, v8, v9, v8
	v_mul_f32_e32 v42, v41, v40
	v_fma_f32 v43, -v23, v42, v41
	v_fmac_f32_e32 v42, v43, v40
	v_fma_f32 v23, -v23, v42, v41
; __device__ __forceinline__ unsigned cvt_pk_bf16(float lo, float hi) { unsigned r; asm volatile("v_cvt_pk_bf16_f32 %0, %1, %2" : "=v"(r) : "v"(lo), "v"(hi)); return r; }
; __device__ __forceinline__ float bflo(unsigned w) { return __uint_as_float(w << 16); }
; __device__ __forceinline__ float bfhi(unsigned w) { return __uint_as_float(w & 0xffff0000u); }
; __device__ __forceinline__ float silu_f(float z) { return z / (1.0f + __expf(-z)); }
; __device__ __forceinline__ void attn_unit(LAS unsigned char* lds, const bf16_t* PROJ, bf16_t* OCAT, const float* subg, float lam, float oml, int b, int h, int qb) {
;     ...
;         for (int i = 0; i < 4; ++i) {
;             const u32x4 z = *(const u32x4*)(zp + 8 * i); const f32x4 ga = *(const f32x4*)(gp + 8 * i), gb = *(const f32x4*)(gp + 8 * i + 4);
;             const f32x4 xa = a[2 * i] * rs * ga, xb = a[2 * i + 1] * rs * gb;
;             u32x4 w; w.x = cvt_pk_bf16(xa.x * silu_f(bflo(z.x)), xa.y * silu_f(bfhi(z.x))); w.y = cvt_pk_bf16(xa.z * silu_f(bflo(z.y)), xa.w * silu_f(bfhi(z.y)));
;             w.z = cvt_pk_bf16(xb.x * silu_f(bflo(z.z)), xb.y * silu_f(bfhi(z.z))); w.w = cvt_pk_bf16(xb.z * silu_f(bflo(z.w)), xb.w * silu_f(bfhi(z.w)));
;             *(u32x4*)(op + 8 * i) = w;
;         }
	v_div_fmas_f32 v23, v23, v40, v42
	v_div_fixup_f32 v8, v23, v9, v8
	v_mul_f32_e32 v9, 0xbfb8aa3b, v1
	v_exp_f32_e32 v9, v9
	v_mul_f32_e32 v8, v8, v10
	v_add_f32_e32 v9, 1.0, v9
	v_div_scale_f32 v10, s[4:5], v9, v9, v1
	v_rcp_f32_e32 v23, v10
	s_nop 0
	v_fma_f32 v40, -v10, v23, 1.0
	v_fmac_f32_e32 v23, v40, v23
	v_div_scale_f32 v40, vcc, v1, v9, v1
	v_mul_f32_e32 v41, v40, v23
	v_fma_f32 v42, -v10, v41, v40
	v_fmac_f32_e32 v41, v42, v23
	v_fma_f32 v10, -v10, v41, v40
	v_div_fmas_f32 v10, v10, v23, v41
	v_div_fixup_f32 v1, v10, v9, v1
	v_mul_f32_e32 v1, v1, v11
	v_cvt_pk_bf16_f32 v1, v8, v1
	v_lshlrev_b32_e32 v8, 16, v2
	v_mul_f32_e32 v9, 0xbfb8aa3b, v8
	v_exp_f32_e32 v9, v9
	v_and_b32_e32 v2, 0xffff0000, v2
	v_add_f32_e32 v9, 1.0, v9
	v_div_scale_f32 v10, s[4:5], v9, v9, v8
	v_rcp_f32_e32 v11, v10
	s_nop 0
	v_fma_f32 v23, -v10, v11, 1.0
	v_fmac_f32_e32 v11, v23, v11
	v_div_scale_f32 v23, vcc, v8, v9, v8
	v_mul_f32_e32 v40, v23, v11
	v_fma_f32 v41, -v10, v40, v23
	v_fmac_f32_e32 v40, v41, v11
	v_fma_f32 v10, -v10, v40, v23
	v_div_fmas_f32 v10, v10, v11, v40
	v_div_fixup_f32 v8, v10, v9, v8
	v_mul_f32_e32 v4, v8, v4
	v_mul_f32_e32 v8, 0xbfb8aa3b, v2
	v_exp_f32_e32 v8, v8
	s_nop 0
	v_add_f32_e32 v8, 1.0, v8
	v_div_scale_f32 v9, s[4:5], v8, v8, v2
	v_rcp_f32_e32 v10, v9
	s_nop 0
	v_fma_f32 v11, -v9, v10, 1.0
	v_fmac_f32_e32 v10, v11, v10
	v_div_scale_f32 v11, vcc, v2, v8, v2
	v_mul_f32_e32 v23, v11, v10
	v_fma_f32 v40, -v9, v23, v11
	v_fmac_f32_e32 v23, v40, v10
	v_fma_f32 v9, -v9, v23, v11
	v_div_fmas_f32 v9, v9, v10, v23
	v_div_fixup_f32 v2, v9, v8, v2
	v_mul_f32_e32 v2, v2, v5
	v_cvt_pk_bf16_f32 v2, v4, v2
	v_lshlrev_b32_e32 v4, 16, v3
	v_mul_f32_e32 v5, 0xbfb8aa3b, v4
	v_exp_f32_e32 v5, v5
	v_and_b32_e32 v3, 0xffff0000, v3
	v_add_f32_e32 v5, 1.0, v5
	v_div_scale_f32 v8, s[4:5], v5, v5, v4
	v_rcp_f32_e32 v9, v8
	s_nop 0
	v_fma_f32 v10, -v8, v9, 1.0
	v_fmac_f32_e32 v9, v10, v9
	v_div_scale_f32 v10, vcc, v4, v5, v4
	v_mul_f32_e32 v11, v10, v9
	v_fma_f32 v23, -v8, v11, v10
	v_fmac_f32_e32 v11, v23, v9
	v_fma_f32 v8, -v8, v11, v10
	v_div_fmas_f32 v8, v8, v9, v11
	v_div_fixup_f32 v4, v8, v5, v4
	v_mul_f32_e32 v5, 0xbfb8aa3b, v3
	v_exp_f32_e32 v5, v5
	v_mul_f32_e32 v4, v4, v6
	v_add_f32_e32 v5, 1.0, v5
	v_div_scale_f32 v6, s[4:5], v5, v5, v3
	v_rcp_f32_e32 v8, v6
	s_nop 0
	v_fma_f32 v9, -v6, v8, 1.0
	v_fmac_f32_e32 v8, v9, v8
	v_div_scale_f32 v9, vcc, v3, v5, v3
	v_mul_f32_e32 v10, v9, v8
	v_fma_f32 v11, -v6, v10, v9
	v_fmac_f32_e32 v10, v11, v8
	v_fma_f32 v6, -v6, v10, v9
	v_div_fmas_f32 v6, v6, v8, v10
	v_div_fixup_f32 v3, v6, v5, v3
	v_mul_f32_e32 v3, v3, v7
	v_cvt_pk_bf16_f32 v3, v4, v3
	global_store_dwordx4 v[64:65], v[0:3], off
	v_pk_mul_f32 v[10:11], v[32:33], v[22:23] op_sel_hi:[1,0]
	v_pk_mul_f32 v[8:9], v[34:35], v[22:23] op_sel_hi:[1,0]
	s_nop 0
	v_mov_b64_e32 v[0:1], v[168:169]
	v_mov_b64_e32 v[2:3], v[170:171]
	v_mov_b64_e32 v[40:41], v[192:193]
	v_mov_b64_e32 v[42:43], v[194:195]
	v_mov_b64_e32 v[4:5], v[188:189]
	v_mov_b64_e32 v[6:7], v[190:191]
	v_pk_mul_f32 v[10:11], v[4:5], v[10:11]
	v_pk_mul_f32 v[8:9], v[6:7], v[8:9]
	v_pk_mul_f32 v[6:7], v[36:37], v[22:23] op_sel_hi:[1,0]
	v_pk_mul_f32 v[4:5], v[38:39], v[22:23] op_sel_hi:[1,0]
	v_lshlrev_b32_e32 v23, 16, v0
	v_mul_f32_e32 v32, 0xbfb8aa3b, v23
	v_exp_f32_e32 v32, v32
	v_and_b32_e32 v0, 0xffff0000, v0
	v_pk_mul_f32 v[6:7], v[40:41], v[6:7]
	v_pk_mul_f32 v[4:5], v[42:43], v[4:5]
	v_add_f32_e32 v32, 1.0, v32
	v_div_scale_f32 v33, s[4:5], v32, v32, v23
	v_rcp_f32_e32 v34, v33
	s_nop 0
	v_fma_f32 v35, -v33, v34, 1.0
	v_fmac_f32_e32 v34, v35, v34
	v_div_scale_f32 v35, vcc, v23, v32, v23
	v_mul_f32_e32 v36, v35, v34
	v_fma_f32 v37, -v33, v36, v35
	v_fmac_f32_e32 v36, v37, v34
	v_fma_f32 v33, -v33, v36, v35
	v_div_fmas_f32 v33, v33, v34, v36
	v_div_fixup_f32 v23, v33, v32, v23
	v_mul_f32_e32 v10, v23, v10
	v_mul_f32_e32 v23, 0xbfb8aa3b, v0
	v_exp_f32_e32 v23, v23
	s_nop 0
	v_add_f32_e32 v23, 1.0, v23
	v_div_scale_f32 v32, s[4:5], v23, v23, v0
	v_rcp_f32_e32 v33, v32
	s_nop 0
	v_fma_f32 v34, -v32, v33, 1.0
	v_fmac_f32_e32 v33, v34, v33
	v_div_scale_f32 v34, vcc, v0, v23, v0
	v_mul_f32_e32 v35, v34, v33
	v_fma_f32 v36, -v32, v35, v34
	v_fmac_f32_e32 v35, v36, v33
	v_fma_f32 v32, -v32, v35, v34
	v_div_fmas_f32 v32, v32, v33, v35
	v_div_fixup_f32 v0, v32, v23, v0
	v_mul_f32_e32 v0, v0, v11
	v_cvt_pk_bf16_f32 v0, v10, v0
	v_lshlrev_b32_e32 v10, 16, v1
	v_mul_f32_e32 v11, 0xbfb8aa3b, v10
	v_exp_f32_e32 v11, v11
	v_and_b32_e32 v1, 0xffff0000, v1
	v_add_f32_e32 v11, 1.0, v11
	v_div_scale_f32 v23, s[4:5], v11, v11, v10
	v_rcp_f32_e32 v32, v23
	s_nop 0
	v_fma_f32 v33, -v23, v32, 1.0
	v_fmac_f32_e32 v32, v33, v32
	v_div_scale_f32 v33, vcc, v10, v11, v10
	v_mul_f32_e32 v34, v33, v32
	v_fma_f32 v35, -v23, v34, v33
	v_fmac_f32_e32 v34, v35, v32
	v_fma_f32 v23, -v23, v34, v33
	v_div_fmas_f32 v23, v23, v32, v34
	v_div_fixup_f32 v10, v23, v11, v10
	v_mul_f32_e32 v8, v10, v8
	v_mul_f32_e32 v10, 0xbfb8aa3b, v1
	v_exp_f32_e32 v10, v10
	s_nop 0
	v_add_f32_e32 v10, 1.0, v10
	v_div_scale_f32 v11, s[4:5], v10, v10, v1
	v_rcp_f32_e32 v23, v11
	s_nop 0
	v_fma_f32 v32, -v11, v23, 1.0
	v_fmac_f32_e32 v23, v32, v23
	v_div_scale_f32 v32, vcc, v1, v10, v1
	v_mul_f32_e32 v33, v32, v23
	v_fma_f32 v34, -v11, v33, v32
	v_fmac_f32_e32 v33, v34, v23
	v_fma_f32 v11, -v11, v33, v32
	v_div_fmas_f32 v11, v11, v23, v33
	v_div_fixup_f32 v1, v11, v10, v1
	v_mul_f32_e32 v1, v1, v9
	v_cvt_pk_bf16_f32 v1, v8, v1
	v_lshlrev_b32_e32 v8, 16, v2
	v_mul_f32_e32 v9, 0xbfb8aa3b, v8
	v_exp_f32_e32 v9, v9
	v_and_b32_e32 v2, 0xffff0000, v2
	v_add_f32_e32 v9, 1.0, v9
	v_div_scale_f32 v10, s[4:5], v9, v9, v8
	v_rcp_f32_e32 v11, v10
; __device__ __forceinline__ unsigned cvt_pk_bf16(float lo, float hi) { unsigned r; asm volatile("v_cvt_pk_bf16_f32 %0, %1, %2" : "=v"(r) : "v"(lo), "v"(hi)); return r; }
; __device__ __forceinline__ float bflo(unsigned w) { return __uint_as_float(w << 16); }
; __device__ __forceinline__ float bfhi(unsigned w) { return __uint_as_float(w & 0xffff0000u); }
; __device__ __forceinline__ float silu_f(float z) { return z / (1.0f + __expf(-z)); }
; __device__ __forceinline__ void attn_unit(LAS unsigned char* lds, const bf16_t* PROJ, bf16_t* OCAT, const float* subg, float lam, float oml, int b, int h, int qb) {
;     ...
;         for (int i = 0; i < 4; ++i) {
;             const u32x4 z = *(const u32x4*)(zp + 8 * i); const f32x4 ga = *(const f32x4*)(gp + 8 * i), gb = *(const f32x4*)(gp + 8 * i + 4);
;             const f32x4 xa = a[2 * i] * rs * ga, xb = a[2 * i + 1] * rs * gb;
;             u32x4 w; w.x = cvt_pk_bf16(xa.x * silu_f(bflo(z.x)), xa.y * silu_f(bfhi(z.x))); w.y = cvt_pk_bf16(xa.z * silu_f(bflo(z.y)), xa.w * silu_f(bfhi(z.y)));
;             w.z = cvt_pk_bf16(xb.x * silu_f(bflo(z.z)), xb.y * silu_f(bfhi(z.z))); w.w = cvt_pk_bf16(xb.z * silu_f(bflo(z.w)), xb.w * silu_f(bfhi(z.w)));
;             *(u32x4*)(op + 8 * i) = w;
;         }
	s_nop 0
	v_fma_f32 v23, -v10, v11, 1.0
	v_fmac_f32_e32 v11, v23, v11
	v_div_scale_f32 v23, vcc, v8, v9, v8
	v_mul_f32_e32 v32, v23, v11
	v_fma_f32 v33, -v10, v32, v23
	v_fmac_f32_e32 v32, v33, v11
	v_fma_f32 v10, -v10, v32, v23
	v_div_fmas_f32 v10, v10, v11, v32
	v_div_fixup_f32 v8, v10, v9, v8
	v_mul_f32_e32 v6, v8, v6
	v_mul_f32_e32 v8, 0xbfb8aa3b, v2
	v_exp_f32_e32 v8, v8
	s_nop 0
	v_add_f32_e32 v8, 1.0, v8
	v_div_scale_f32 v9, s[4:5], v8, v8, v2
	v_rcp_f32_e32 v10, v9
	s_nop 0
	v_fma_f32 v11, -v9, v10, 1.0
	v_fmac_f32_e32 v10, v11, v10
	v_div_scale_f32 v11, vcc, v2, v8, v2
	v_mul_f32_e32 v23, v11, v10
	v_fma_f32 v32, -v9, v23, v11
	v_fmac_f32_e32 v23, v32, v10
	v_fma_f32 v9, -v9, v23, v11
	v_div_fmas_f32 v9, v9, v10, v23
	v_div_fixup_f32 v2, v9, v8, v2
	v_mul_f32_e32 v2, v2, v7
	v_cvt_pk_bf16_f32 v2, v6, v2
	v_lshlrev_b32_e32 v6, 16, v3
	v_mul_f32_e32 v7, 0xbfb8aa3b, v6
	v_exp_f32_e32 v7, v7
	v_and_b32_e32 v3, 0xffff0000, v3
	v_add_f32_e32 v7, 1.0, v7
	v_div_scale_f32 v8, s[4:5], v7, v7, v6
	v_rcp_f32_e32 v9, v8
	s_nop 0
	v_fma_f32 v10, -v8, v9, 1.0
	v_fmac_f32_e32 v9, v10, v9
	v_div_scale_f32 v10, vcc, v6, v7, v6
	v_mul_f32_e32 v11, v10, v9
	v_fma_f32 v23, -v8, v11, v10
	v_fmac_f32_e32 v11, v23, v9
	v_fma_f32 v8, -v8, v11, v10
	v_div_fmas_f32 v8, v8, v9, v11
	v_div_fixup_f32 v6, v8, v7, v6
	v_mul_f32_e32 v4, v6, v4
	v_mul_f32_e32 v6, 0xbfb8aa3b, v3
	v_exp_f32_e32 v6, v6
	s_nop 0
	v_add_f32_e32 v6, 1.0, v6
	v_div_scale_f32 v7, s[4:5], v6, v6, v3
	v_rcp_f32_e32 v8, v7
	s_nop 0
	v_fma_f32 v9, -v7, v8, 1.0
	v_fmac_f32_e32 v8, v9, v8
	v_div_scale_f32 v9, vcc, v3, v6, v3
	v_mul_f32_e32 v10, v9, v8
	v_fma_f32 v11, -v7, v10, v9
	v_fmac_f32_e32 v10, v11, v8
	v_fma_f32 v7, -v7, v10, v9
	v_div_fmas_f32 v7, v7, v8, v10
	v_div_fixup_f32 v3, v7, v6, v3
	v_mul_f32_e32 v3, v3, v5
	v_cvt_pk_bf16_f32 v3, v4, v3
	global_store_dwordx4 v[64:65], v[0:3], off offset:16
	v_pk_mul_f32 v[10:11], v[26:27], v[22:23] op_sel_hi:[1,0]
	v_pk_mul_f32 v[8:9], v[24:25], v[22:23] op_sel_hi:[1,0]
	s_nop 0
	v_mov_b64_e32 v[0:1], v[172:173]
	v_mov_b64_e32 v[2:3], v[174:175]
	v_mov_b64_e32 v[32:33], v[200:201]
	v_mov_b64_e32 v[34:35], v[202:203]
	v_mov_b64_e32 v[4:5], v[196:197]
	v_mov_b64_e32 v[6:7], v[198:199]
	v_pk_mul_f32 v[10:11], v[4:5], v[10:11]
	v_pk_mul_f32 v[8:9], v[6:7], v[8:9]
	v_pk_mul_f32 v[6:7], v[28:29], v[22:23] op_sel_hi:[1,0]
	v_pk_mul_f32 v[4:5], v[30:31], v[22:23] op_sel_hi:[1,0]
	v_lshlrev_b32_e32 v23, 16, v0
	v_mul_f32_e32 v24, 0xbfb8aa3b, v23
	v_exp_f32_e32 v24, v24
	v_and_b32_e32 v0, 0xffff0000, v0
	v_pk_mul_f32 v[6:7], v[6:7], v[32:33]
	v_pk_mul_f32 v[4:5], v[4:5], v[34:35]
	v_add_f32_e32 v24, 1.0, v24
	v_div_scale_f32 v25, s[4:5], v24, v24, v23
	v_rcp_f32_e32 v26, v25
	s_nop 0
	v_fma_f32 v27, -v25, v26, 1.0
	v_fmac_f32_e32 v26, v27, v26
	v_div_scale_f32 v27, vcc, v23, v24, v23
	v_mul_f32_e32 v28, v27, v26
	v_fma_f32 v29, -v25, v28, v27
	v_fmac_f32_e32 v28, v29, v26
	v_fma_f32 v25, -v25, v28, v27
	v_div_fmas_f32 v25, v25, v26, v28
	v_div_fixup_f32 v23, v25, v24, v23
	v_mul_f32_e32 v10, v10, v23
	v_mul_f32_e32 v23, 0xbfb8aa3b, v0
	v_exp_f32_e32 v23, v23
	s_nop 0
	v_add_f32_e32 v23, 1.0, v23
	v_div_scale_f32 v24, s[4:5], v23, v23, v0
	v_rcp_f32_e32 v25, v24
	s_nop 0
	v_fma_f32 v26, -v24, v25, 1.0
	v_fmac_f32_e32 v25, v26, v25
	v_div_scale_f32 v26, vcc, v0, v23, v0
	v_mul_f32_e32 v27, v26, v25
	v_fma_f32 v28, -v24, v27, v26
	v_fmac_f32_e32 v27, v28, v25
	v_fma_f32 v24, -v24, v27, v26
	v_div_fmas_f32 v24, v24, v25, v27
	v_div_fixup_f32 v0, v24, v23, v0
	v_mul_f32_e32 v0, v11, v0
	v_cvt_pk_bf16_f32 v0, v10, v0
	v_lshlrev_b32_e32 v10, 16, v1
	v_mul_f32_e32 v11, 0xbfb8aa3b, v10
	v_exp_f32_e32 v11, v11
	v_and_b32_e32 v1, 0xffff0000, v1
	v_add_f32_e32 v11, 1.0, v11
	v_div_scale_f32 v23, s[4:5], v11, v11, v10
	v_rcp_f32_e32 v24, v23
	s_nop 0
	v_fma_f32 v25, -v23, v24, 1.0
	v_fmac_f32_e32 v24, v25, v24
	v_div_scale_f32 v25, vcc, v10, v11, v10
	v_mul_f32_e32 v26, v25, v24
	v_fma_f32 v27, -v23, v26, v25
	v_fmac_f32_e32 v26, v27, v24
	v_fma_f32 v23, -v23, v26, v25
	v_div_fmas_f32 v23, v23, v24, v26
	v_div_fixup_f32 v10, v23, v11, v10
	v_mul_f32_e32 v8, v8, v10
	v_mul_f32_e32 v10, 0xbfb8aa3b, v1
	v_exp_f32_e32 v10, v10
	s_nop 0
	v_add_f32_e32 v10, 1.0, v10
	v_div_scale_f32 v11, s[4:5], v10, v10, v1
	v_rcp_f32_e32 v23, v11
	s_nop 0
	v_fma_f32 v24, -v11, v23, 1.0
	v_fmac_f32_e32 v23, v24, v23
	v_div_scale_f32 v24, vcc, v1, v10, v1
	v_mul_f32_e32 v25, v24, v23
	v_fma_f32 v26, -v11, v25, v24
	v_fmac_f32_e32 v25, v26, v23
	v_fma_f32 v11, -v11, v25, v24
	v_div_fmas_f32 v11, v11, v23, v25
	v_div_fixup_f32 v1, v11, v10, v1
	v_mul_f32_e32 v1, v9, v1
	v_cvt_pk_bf16_f32 v1, v8, v1
	v_lshlrev_b32_e32 v8, 16, v2
	v_mul_f32_e32 v9, 0xbfb8aa3b, v8
	v_exp_f32_e32 v9, v9
	v_and_b32_e32 v2, 0xffff0000, v2
	v_add_f32_e32 v9, 1.0, v9
	v_div_scale_f32 v10, s[4:5], v9, v9, v8
	v_rcp_f32_e32 v11, v10
	s_nop 0
	v_fma_f32 v23, -v10, v11, 1.0
	v_fmac_f32_e32 v11, v23, v11
	v_div_scale_f32 v23, vcc, v8, v9, v8
	v_mul_f32_e32 v24, v23, v11
	v_fma_f32 v25, -v10, v24, v23
	v_fmac_f32_e32 v24, v25, v11
	v_fma_f32 v10, -v10, v24, v23
	v_div_fmas_f32 v10, v10, v11, v24
	v_div_fixup_f32 v8, v10, v9, v8
	v_mul_f32_e32 v6, v6, v8
	v_mul_f32_e32 v8, 0xbfb8aa3b, v2
	v_exp_f32_e32 v8, v8
	s_nop 0
	v_add_f32_e32 v8, 1.0, v8
	v_div_scale_f32 v9, s[4:5], v8, v8, v2
	v_rcp_f32_e32 v10, v9
	s_nop 0
	v_fma_f32 v11, -v9, v10, 1.0
	v_fmac_f32_e32 v10, v11, v10
	v_div_scale_f32 v11, vcc, v2, v8, v2
	v_mul_f32_e32 v23, v11, v10
	v_fma_f32 v24, -v9, v23, v11
	v_fmac_f32_e32 v23, v24, v10
	v_fma_f32 v9, -v9, v23, v11
	v_div_fmas_f32 v9, v9, v10, v23
	v_div_fixup_f32 v2, v9, v8, v2
	v_mul_f32_e32 v2, v7, v2
; __device__ __forceinline__ unsigned cvt_pk_bf16(float lo, float hi) { unsigned r; asm volatile("v_cvt_pk_bf16_f32 %0, %1, %2" : "=v"(r) : "v"(lo), "v"(hi)); return r; }
; __device__ __forceinline__ float bflo(unsigned w) { return __uint_as_float(w << 16); }
; __device__ __forceinline__ float bfhi(unsigned w) { return __uint_as_float(w & 0xffff0000u); }
; __device__ __forceinline__ float silu_f(float z) { return z / (1.0f + __expf(-z)); }
; __device__ __forceinline__ void attn_unit(LAS unsigned char* lds, const bf16_t* PROJ, bf16_t* OCAT, const float* subg, float lam, float oml, int b, int h, int qb) {
;     ...
;         for (int i = 0; i < 4; ++i) {
;             const u32x4 z = *(const u32x4*)(zp + 8 * i); const f32x4 ga = *(const f32x4*)(gp + 8 * i), gb = *(const f32x4*)(gp + 8 * i + 4);
;             const f32x4 xa = a[2 * i] * rs * ga, xb = a[2 * i + 1] * rs * gb;
;             u32x4 w; w.x = cvt_pk_bf16(xa.x * silu_f(bflo(z.x)), xa.y * silu_f(bfhi(z.x))); w.y = cvt_pk_bf16(xa.z * silu_f(bflo(z.y)), xa.w * silu_f(bfhi(z.y)));
;             w.z = cvt_pk_bf16(xb.x * silu_f(bflo(z.z)), xb.y * silu_f(bfhi(z.z))); w.w = cvt_pk_bf16(xb.z * silu_f(bflo(z.w)), xb.w * silu_f(bfhi(z.w)));
;             *(u32x4*)(op + 8 * i) = w;
;         }
;     }
;     __syncthreads();
;     }
; }
	v_cvt_pk_bf16_f32 v2, v6, v2
	v_lshlrev_b32_e32 v6, 16, v3
	v_mul_f32_e32 v7, 0xbfb8aa3b, v6
	v_exp_f32_e32 v7, v7
	v_and_b32_e32 v3, 0xffff0000, v3
	v_add_f32_e32 v7, 1.0, v7
	v_div_scale_f32 v8, s[4:5], v7, v7, v6
	v_rcp_f32_e32 v9, v8
	s_nop 0
	v_fma_f32 v10, -v8, v9, 1.0
	v_fmac_f32_e32 v9, v10, v9
	v_div_scale_f32 v10, vcc, v6, v7, v6
	v_mul_f32_e32 v11, v10, v9
	v_fma_f32 v23, -v8, v11, v10
	v_fmac_f32_e32 v11, v23, v9
	v_fma_f32 v8, -v8, v11, v10
	v_div_fmas_f32 v8, v8, v9, v11
	v_div_fixup_f32 v6, v8, v7, v6
	v_mul_f32_e32 v4, v4, v6
	v_mul_f32_e32 v6, 0xbfb8aa3b, v3
	v_exp_f32_e32 v6, v6
	v_pk_mul_f32 v[14:15], v[14:15], v[22:23] op_sel_hi:[1,0]
	v_add_f32_e32 v6, 1.0, v6
	v_div_scale_f32 v7, s[4:5], v6, v6, v3
	v_rcp_f32_e32 v8, v7
	s_nop 0
	v_fma_f32 v9, -v7, v8, 1.0
	v_fmac_f32_e32 v8, v9, v8
	v_div_scale_f32 v9, vcc, v3, v6, v3
	v_mul_f32_e32 v10, v9, v8
	v_fma_f32 v11, -v7, v10, v9
	v_fmac_f32_e32 v10, v11, v8
	v_fma_f32 v7, -v7, v10, v9
	v_div_fmas_f32 v7, v7, v8, v10
	v_div_fixup_f32 v3, v7, v6, v3
	v_mul_f32_e32 v3, v5, v3
	v_cvt_pk_bf16_f32 v3, v4, v3
	global_store_dwordx4 v[64:65], v[0:3], off offset:32
	v_pk_mul_f32 v[8:9], v[16:17], v[22:23] op_sel_hi:[1,0]
	s_nop 0
	v_mov_b64_e32 v[0:1], v[176:177]
	v_mov_b64_e32 v[2:3], v[178:179]
	v_mov_b64_e32 v[10:11], v[208:209]
	v_mov_b64_e32 v[12:13], v[210:211]
	v_mov_b64_e32 v[4:5], v[204:205]
	v_mov_b64_e32 v[6:7], v[206:207]
	v_pk_mul_f32 v[14:15], v[14:15], v[4:5]
	v_pk_mul_f32 v[8:9], v[8:9], v[6:7]
	v_pk_mul_f32 v[6:7], v[20:21], v[22:23] op_sel_hi:[1,0]
	v_pk_mul_f32 v[4:5], v[18:19], v[22:23] op_sel_hi:[1,0]
	v_pk_mul_f32 v[6:7], v[6:7], v[10:11]
	v_lshlrev_b32_e32 v10, 16, v0
	v_mul_f32_e32 v11, 0xbfb8aa3b, v10
	v_exp_f32_e32 v11, v11
	v_pk_mul_f32 v[4:5], v[4:5], v[12:13]
	v_and_b32_e32 v0, 0xffff0000, v0
	v_add_f32_e32 v11, 1.0, v11
	v_div_scale_f32 v12, s[4:5], v11, v11, v10
	v_rcp_f32_e32 v13, v12
	s_nop 0
	v_fma_f32 v16, -v12, v13, 1.0
	v_fmac_f32_e32 v13, v16, v13
	v_div_scale_f32 v16, vcc, v10, v11, v10
	v_mul_f32_e32 v17, v16, v13
	v_fma_f32 v18, -v12, v17, v16
	v_fmac_f32_e32 v17, v18, v13
	v_fma_f32 v12, -v12, v17, v16
	v_div_fmas_f32 v12, v12, v13, v17
	v_div_fixup_f32 v10, v12, v11, v10
	v_mul_f32_e32 v11, 0xbfb8aa3b, v0
	v_exp_f32_e32 v11, v11
	v_mul_f32_e32 v10, v14, v10
	v_add_f32_e32 v11, 1.0, v11
	v_div_scale_f32 v12, s[4:5], v11, v11, v0
	v_rcp_f32_e32 v13, v12
	s_nop 0
	v_fma_f32 v14, -v12, v13, 1.0
	v_fmac_f32_e32 v13, v14, v13
	v_div_scale_f32 v14, vcc, v0, v11, v0
	v_mul_f32_e32 v16, v14, v13
	v_fma_f32 v17, -v12, v16, v14
	v_fmac_f32_e32 v16, v17, v13
	v_fma_f32 v12, -v12, v16, v14
	v_div_fmas_f32 v12, v12, v13, v16
	v_div_fixup_f32 v0, v12, v11, v0
	v_mul_f32_e32 v0, v15, v0
	v_cvt_pk_bf16_f32 v0, v10, v0
	v_lshlrev_b32_e32 v10, 16, v1
	v_mul_f32_e32 v11, 0xbfb8aa3b, v10
	v_exp_f32_e32 v11, v11
	v_and_b32_e32 v1, 0xffff0000, v1
	v_add_f32_e32 v11, 1.0, v11
	v_div_scale_f32 v12, s[4:5], v11, v11, v10
	v_rcp_f32_e32 v13, v12
	s_nop 0
	v_fma_f32 v14, -v12, v13, 1.0
	v_fmac_f32_e32 v13, v14, v13
	v_div_scale_f32 v14, vcc, v10, v11, v10
	v_mul_f32_e32 v15, v14, v13
	v_fma_f32 v16, -v12, v15, v14
	v_fmac_f32_e32 v15, v16, v13
	v_fma_f32 v12, -v12, v15, v14
	v_div_fmas_f32 v12, v12, v13, v15
	v_div_fixup_f32 v10, v12, v11, v10
	v_mul_f32_e32 v8, v8, v10
	v_mul_f32_e32 v10, 0xbfb8aa3b, v1
	v_exp_f32_e32 v10, v10
	s_nop 0
	v_add_f32_e32 v10, 1.0, v10
	v_div_scale_f32 v11, s[4:5], v10, v10, v1
	v_rcp_f32_e32 v12, v11
	s_nop 0
	v_fma_f32 v13, -v11, v12, 1.0
	v_fmac_f32_e32 v12, v13, v12
	v_div_scale_f32 v13, vcc, v1, v10, v1
	v_mul_f32_e32 v14, v13, v12
	v_fma_f32 v15, -v11, v14, v13
	v_fmac_f32_e32 v14, v15, v12
	v_fma_f32 v11, -v11, v14, v13
	v_div_fmas_f32 v11, v11, v12, v14
	v_div_fixup_f32 v1, v11, v10, v1
	v_mul_f32_e32 v1, v9, v1
	v_cvt_pk_bf16_f32 v1, v8, v1
	v_lshlrev_b32_e32 v8, 16, v2
	v_mul_f32_e32 v9, 0xbfb8aa3b, v8
	v_exp_f32_e32 v9, v9
	v_and_b32_e32 v2, 0xffff0000, v2
	v_add_f32_e32 v9, 1.0, v9
	v_div_scale_f32 v10, s[4:5], v9, v9, v8
	v_rcp_f32_e32 v11, v10
	s_nop 0
	v_fma_f32 v12, -v10, v11, 1.0
	v_fmac_f32_e32 v11, v12, v11
	v_div_scale_f32 v12, vcc, v8, v9, v8
	v_mul_f32_e32 v13, v12, v11
	v_fma_f32 v14, -v10, v13, v12
	v_fmac_f32_e32 v13, v14, v11
	v_fma_f32 v10, -v10, v13, v12
	v_div_fmas_f32 v10, v10, v11, v13
	v_div_fixup_f32 v8, v10, v9, v8
	v_mul_f32_e32 v6, v6, v8
	v_mul_f32_e32 v8, 0xbfb8aa3b, v2
	v_exp_f32_e32 v8, v8
	s_nop 0
	v_add_f32_e32 v8, 1.0, v8
	v_div_scale_f32 v9, s[4:5], v8, v8, v2
	v_rcp_f32_e32 v10, v9
	s_nop 0
	v_fma_f32 v11, -v9, v10, 1.0
	v_fmac_f32_e32 v10, v11, v10
	v_div_scale_f32 v11, vcc, v2, v8, v2
	v_mul_f32_e32 v12, v11, v10
	v_fma_f32 v13, -v9, v12, v11
	v_fmac_f32_e32 v12, v13, v10
	v_fma_f32 v9, -v9, v12, v11
	v_div_fmas_f32 v9, v9, v10, v12
	v_div_fixup_f32 v2, v9, v8, v2
	v_mul_f32_e32 v2, v7, v2
	v_cvt_pk_bf16_f32 v2, v6, v2
	v_lshlrev_b32_e32 v6, 16, v3
	v_mul_f32_e32 v7, 0xbfb8aa3b, v6
	v_exp_f32_e32 v7, v7
	v_and_b32_e32 v3, 0xffff0000, v3
	v_add_f32_e32 v7, 1.0, v7
	v_div_scale_f32 v8, s[4:5], v7, v7, v6
	v_rcp_f32_e32 v9, v8
	s_nop 0
	v_fma_f32 v10, -v8, v9, 1.0
	v_fmac_f32_e32 v9, v10, v9
	v_div_scale_f32 v10, vcc, v6, v7, v6
	v_mul_f32_e32 v11, v10, v9
	v_fma_f32 v12, -v8, v11, v10
	v_fmac_f32_e32 v11, v12, v9
	v_fma_f32 v8, -v8, v11, v10
	v_div_fmas_f32 v8, v8, v9, v11
	v_div_fixup_f32 v6, v8, v7, v6
	v_mul_f32_e32 v4, v4, v6
	v_mul_f32_e32 v6, 0xbfb8aa3b, v3
	v_exp_f32_e32 v6, v6
	s_nop 0
	v_add_f32_e32 v6, 1.0, v6
	v_div_scale_f32 v7, s[4:5], v6, v6, v3
	v_rcp_f32_e32 v8, v7
	s_nop 0
	v_fma_f32 v9, -v7, v8, 1.0
	v_fmac_f32_e32 v8, v9, v8
	v_div_scale_f32 v9, vcc, v3, v6, v3
	v_mul_f32_e32 v10, v9, v8
	v_fma_f32 v11, -v7, v10, v9
	v_fmac_f32_e32 v10, v11, v8
	v_fma_f32 v7, -v7, v10, v9
	v_div_fmas_f32 v7, v7, v8, v10
	v_div_fixup_f32 v3, v7, v6, v3
	v_mul_f32_e32 v3, v5, v3
	v_cvt_pk_bf16_f32 v3, v4, v3
	global_store_dwordx4 v[64:65], v[0:3], off offset:48
	s_barrier
	s_cbranch_scc1 .LBB0_473

; __device__ __forceinline__ void attn_unit(LAS unsigned char* lds, const bf16_t* PROJ, bf16_t* OCAT, const float* subg, float lam, float oml, int b, int h, int qb) {
;     ...
;         const bf16_t* zp = PROJ + row * PP + C_ZA + h * 128 + part * 32; bf16_t* op = OCAT + row * 2048 + h * 128 + part * 32; const float* gp = subg + part * 32;
.LBB0_468:
	s_waitcnt vmcnt(3)
	v_or_b32_e32 v112, 0x9000, v245
	v_add_u32_e32 v160, 0, v112
	s_waitcnt vmcnt(0)
	v_lshrrev_b32_e32 v161, 2, v234
	v_add_u32_e32 v161, s82, v161
	v_mul_u32_u24_e32 v161, 0x2800, v161
	v_lshlrev_b32_e32 v162, 6, v234
	v_and_b32_e32 v162, 0xc0, v162
	v_mov_b32_e32 v163, s69
	v_lshl_add_u32 v162, v163, 1, v162
	v_add_u32_e32 v161, v161, v162
	v_add_u32_e32 v161, 0x1800, v161
	global_load_dwordx4 v[164:167], v161, s[6:7]
	global_load_dwordx4 v[168:171], v161, s[6:7] offset:16
	global_load_dwordx4 v[172:175], v161, s[6:7] offset:32
	global_load_dwordx4 v[176:179], v161, s[6:7] offset:48
	v_mfma_f32_32x32x16_bf16 v[112:127], v[220:223], v[156:159], v[64:79]
	v_add_f32_e32 v128, v96, v98
	v_add_f32_e32 v129, v97, v99
	v_add_f32_e32 v132, v100, v128
	v_add_f32_e32 v133, v101, v129
	v_cvt_pk_bf16_f32 v128, v96, v97
	v_cvt_pk_bf16_f32 v129, v98, v99
	v_mfma_f32_32x32x16_bf16 v[64:79], v[216:219], v[156:159], v[64:79]
	v_add_f32_e32 v96, v102, v132
	v_add_f32_e32 v97, v103, v133
	v_add_f32_e32 v96, v104, v96
	v_add_f32_e32 v97, v105, v97
	v_cvt_pk_bf16_f32 v130, v100, v101
	v_cvt_pk_bf16_f32 v131, v102, v103
	v_mfma_f32_32x32x16_bf16 v[112:127], v[212:215], v[152:155], v[112:127]
	v_add_f32_e32 v96, v106, v96
	v_add_f32_e32 v97, v107, v97
	v_add_f32_e32 v96, v108, v96
	v_add_f32_e32 v97, v109, v97
	v_cvt_pk_bf16_f32 v104, v104, v105
	v_cvt_pk_bf16_f32 v105, v106, v107
	v_mfma_f32_32x32x16_bf16 v[64:79], v[208:211], v[152:155], v[64:79]
	v_add_f32_e32 v96, v110, v96
	v_add_f32_e32 v97, v111, v97
	v_add_f32_e32 v96, v80, v96
	v_add_f32_e32 v97, v81, v97
	v_cvt_pk_bf16_f32 v106, v108, v109
	v_cvt_pk_bf16_f32 v107, v110, v111
	v_mfma_f32_32x32x16_bf16 v[112:127], v[204:207], v[148:151], v[112:127]
	ds_read_b64_tr_b16 v[140:141], v160 offset:40960
	ds_read_b64_tr_b16 v[142:143], v160 offset:43520
	v_add_f32_e32 v96, v82, v96
	v_add_f32_e32 v97, v83, v97
	v_add_f32_e32 v96, v84, v96
	v_add_f32_e32 v97, v85, v97
	v_cvt_pk_bf16_f32 v100, v80, v81
	v_cvt_pk_bf16_f32 v101, v82, v83
	v_mfma_f32_32x32x16_bf16 v[64:79], v[200:203], v[148:151], v[64:79]
	ds_read_b64_tr_b16 v[136:137], v160 offset:41024
	ds_read_b64_tr_b16 v[138:139], v160 offset:43584
	v_add_f32_e32 v80, v86, v96
	v_add_f32_e32 v81, v87, v97
	v_add_f32_e32 v80, v88, v80
	v_add_f32_e32 v81, v89, v81
	v_cvt_pk_bf16_f32 v102, v84, v85
	v_cvt_pk_bf16_f32 v103, v86, v87
	v_mfma_f32_32x32x16_bf16 v[112:127], v[196:199], v[144:147], v[112:127]
	ds_read_b64_tr_b16 v[132:133], v160 offset:41088
	ds_read_b64_tr_b16 v[134:135], v160 offset:43648
	v_add_f32_e32 v80, v90, v80
	v_add_f32_e32 v81, v91, v81
	v_add_f32_e32 v80, v92, v80
	v_add_f32_e32 v81, v93, v81
	v_cvt_pk_bf16_f32 v96, v88, v89
	v_cvt_pk_bf16_f32 v97, v90, v91
	v_mfma_f32_32x32x16_bf16 v[64:79], v[192:195], v[144:147], v[64:79]
	ds_read_b64_tr_b16 v[108:109], v160 offset:41152
	ds_read_b64_tr_b16 v[110:111], v160 offset:43712
	v_add_f32_e32 v80, v94, v80
	v_add_f32_e32 v81, v95, v81
	v_add_f32_e32 v80, 0, v80
	v_add_f32_e32 v81, 0, v81
	v_cvt_pk_bf16_f32 v98, v92, v93
	v_cvt_pk_bf16_f32 v99, v94, v95
	s_nop 0
	v_add_f32_e32 v80, v80, v81
	s_nop 3
	v_add_f32_e32 v145, v247, v80
	v_max3_f32 v81, v112, v113, v64
	v_max3_f32 v82, v114, v115, v65
	v_max3_f32 v81, v81, v66, v67
	v_max3_f32 v82, v82, v118, v119
	v_max3_f32 v81, v81, v116, v117
	v_max3_f32 v82, v82, v70, v71
	v_max3_f32 v81, v81, v68, v69
	v_max3_f32 v82, v82, v122, v123
	v_max3_f32 v81, v81, v120, v121
	v_max3_f32 v82, v82, v74, v75
	v_max3_f32 v81, v81, v72, v73
	v_max3_f32 v82, v82, v126, v127
	v_max3_f32 v81, v81, v124, v125
	v_max3_f32 v82, v82, v78, v79
	v_max3_f32 v81, v81, v76, v77
	v_max_f32_e32 v80, v81, v82
	v_mov_b32_e32 v81, v80
	s_nop 1
	v_permlane32_swap_b32_e32 v80, v81
	v_max_f32_e32 v80, v80, v81
	v_cmp_lt_f32_e32 vcc, s61, v80
	s_cbranch_vccnz .LBB0_472
	v_mov_b32_e32 v144, 1.0
